# removed the compiler's stray s_waitcnt vmcnt(0) at the head of the q_b GEMM K-loop (only loop copy that drained the LDS-DMA prefetch each iteration), on top of one-barrier attention + early inv
# speedup vs baseline: 1.0021x; 1.0021x over previous
; #define PG8_STAGE(bufoff, gbase, voff) do { _Pragma("unroll") for (int _i = 0; _i < 2; ++_i) \
;         __builtin_amdgcn_global_load_lds((const unsigned*)((const char*)(gbase) + (voff)[_i]), (PG8_LAS unsigned*)(lds + (bufoff) + ldsw + _i * 8192), 16, 0, 0); } while (0)
; #define PG8_LDA(dst, b, h) do { _Pragma("unroll") for (int m = 0; m < 4; ++m) _Pragma("unroll") for (int k = 0; k < 2; ++k) dst[m][k] = *(const PG8_LAS bf16x8*)(lds + PG8_SA(b, h) + aoff + m * 2048 + k * 1024); } while (0)
; #define PG8_LDB(dst, b, h) do { _Pragma("unroll") for (int n = 0; n < 2; ++n) _Pragma("unroll") for (int k = 0; k < 2; ++k) dst[n][k] = *(const PG8_LAS bf16x8*)(lds + PG8_SB(b, h) + boff + n * 2048 + k * 1024); } while (0)
; #define PG8_MMA(ai, bj, At, Bt) do { __builtin_amdgcn_s_setprio(1); _Pragma("unroll") for (int m = 0; m < 4; ++m) _Pragma("unroll") for (int n = 0; n < 2; ++n) _Pragma("unroll") for (int k = 0; k < 2; ++k) \
;         acc[ai][bj][m][n] = __builtin_amdgcn_mfma_f32_16x16x32_bf16(Bt[n][k], At[m][k], acc[ai][bj][m][n], 0, 0, 0); __builtin_amdgcn_s_setprio(0); } while (0)
; #define PG8_WAIT_V(n) asm volatile("s_waitcnt vmcnt(" #n ")" ::: "memory")
; #define PG8_WAIT_L(n) asm volatile("s_waitcnt lgkmcnt(" #n ")" ::: "memory")
; #define PG8_BAR __builtin_amdgcn_s_barrier()
; #define PG8_SCHED __builtin_amdgcn_sched_barrier(0)
; template <class Epi, class Sched, bool ALIGN_EPI = false, bool SP2 = false>
; __device__ __forceinline__ void gemm_phase(PG8_LAS unsigned char* lds, const Gemm g, const Sched& S, const Epi& E) {
;     ...
;             PG8_LDB(B0, 0, 0); PG8_LDB(B1, 0, 1); PG8_SCHED; PG8_LDA(At, 0, 0); PG8_STAGE(PG8_SA(1, 1), a1 + hstep, voffA);
;             PG8_WAIT_V(8); PG8_WAIT_L(0); PG8_BAR; PG8_MMA(0, 0, At, B0); PG8_MMA(0, 1, At, B1); PG8_BAR; PG8_SCHED;
;             PG8_LDA(At, 0, 1); PG8_STAGE(PG8_SB(0, 0), b2, voffB); PG8_STAGE(PG8_SB(0, 1), b2 + hstep, voffB); PG8_STAGE(PG8_SA(0, 0), a2, voffA);
;             PG8_WAIT_V(8); PG8_WAIT_L(0); PG8_BAR; PG8_MMA(1, 0, At, B0); PG8_MMA(1, 1, At, B1); PG8_BAR; PG8_SCHED;
.LBB0_382:
	ds_read_b128 v[128:131], v230
	ds_read_b128 v[132:135], v230 offset:1024
	ds_read_b128 v[136:139], v230 offset:2048
	ds_read_b128 v[140:143], v230 offset:3072
	ds_read_b128 v[144:147], v231
	ds_read_b128 v[148:151], v231 offset:1024
	ds_read_b128 v[152:155], v231 offset:2048
	ds_read_b128 v[156:159], v231 offset:3072
	s_add_u32 s0, s56, 0x100
	s_addc_u32 s1, s57, 0
	s_cmp_eq_u32 s82, 8
	s_cselect_b32 s61, s49, s1
	s_cselect_b32 s60, s48, s0
	s_cselect_b32 s59, s55, s81
	s_cselect_b32 s58, s54, s80
	v_lshl_add_u64 v[220:221], s[56:57], 0, v[204:205]
	s_add_i32 m0, s25, 0xc000
	ds_read_b128 v[160:163], v232
	ds_read_b128 v[164:167], v232 offset:1024
	ds_read_b128 v[168:171], v232 offset:2048
	ds_read_b128 v[172:175], v232 offset:3072
	ds_read_b128 v[176:179], v232 offset:4096
	ds_read_b128 v[180:183], v232 offset:5120
	ds_read_b128 v[212:215], v232 offset:6144
	ds_read_b128 v[216:219], v232 offset:7168
	global_load_lds_dwordx4 v[220:221], off
	v_lshl_add_u64 v[220:221], s[56:57], 0, v[206:207]
	s_add_i32 m0, s25, 0xe000
	s_nop 0
	global_load_lds_dwordx4 v[220:221], off
	s_waitcnt vmcnt(8)
	s_waitcnt lgkmcnt(0)
	s_barrier
	s_setprio 1
	s_waitcnt lgkmcnt(0)
	v_mfma_f32_16x16x32_bf16 v[124:127], v[128:131], v[160:163], v[124:127]
	v_mfma_f32_16x16x32_bf16 v[120:123], v[136:139], v[160:163], v[120:123]
	v_mfma_f32_16x16x32_bf16 v[108:111], v[128:131], v[168:171], v[108:111]
	v_mfma_f32_16x16x32_bf16 v[104:107], v[136:139], v[168:171], v[104:107]
	v_mfma_f32_16x16x32_bf16 v[92:95], v[128:131], v[176:179], v[92:95]
	v_mfma_f32_16x16x32_bf16 v[88:91], v[136:139], v[176:179], v[88:91]
	v_mfma_f32_16x16x32_bf16 v[76:79], v[128:131], v[212:215], v[76:79]
	v_mfma_f32_16x16x32_bf16 v[72:75], v[136:139], v[212:215], v[72:75]
	v_mfma_f32_16x16x32_bf16 v[124:127], v[132:135], v[164:167], v[124:127]
	v_mfma_f32_16x16x32_bf16 v[120:123], v[140:143], v[164:167], v[120:123]
	v_mfma_f32_16x16x32_bf16 v[108:111], v[132:135], v[172:175], v[108:111]
	v_mfma_f32_16x16x32_bf16 v[104:107], v[140:143], v[172:175], v[104:107]
	v_mfma_f32_16x16x32_bf16 v[92:95], v[132:135], v[180:183], v[92:95]
	v_mfma_f32_16x16x32_bf16 v[88:91], v[140:143], v[180:183], v[88:91]
	v_mfma_f32_16x16x32_bf16 v[76:79], v[132:135], v[216:219], v[76:79]
	v_mfma_f32_16x16x32_bf16 v[72:75], v[140:143], v[216:219], v[72:75]
	s_setprio 0
	s_setprio 1
	v_mfma_f32_16x16x32_bf16 v[116:119], v[144:147], v[160:163], v[116:119]
	v_mfma_f32_16x16x32_bf16 v[112:115], v[152:155], v[160:163], v[112:115]
	v_mfma_f32_16x16x32_bf16 v[100:103], v[144:147], v[168:171], v[100:103]
	v_mfma_f32_16x16x32_bf16 v[96:99], v[152:155], v[168:171], v[96:99]
	v_mfma_f32_16x16x32_bf16 v[84:87], v[144:147], v[176:179], v[84:87]
	v_mfma_f32_16x16x32_bf16 v[80:83], v[152:155], v[176:179], v[80:83]
	v_mfma_f32_16x16x32_bf16 v[68:71], v[144:147], v[212:215], v[68:71]
	v_mfma_f32_16x16x32_bf16 v[64:67], v[152:155], v[212:215], v[64:67]
	v_mfma_f32_16x16x32_bf16 v[116:119], v[148:151], v[164:167], v[116:119]
	v_mfma_f32_16x16x32_bf16 v[112:115], v[156:159], v[164:167], v[112:115]
	v_mfma_f32_16x16x32_bf16 v[100:103], v[148:151], v[172:175], v[100:103]
	v_mfma_f32_16x16x32_bf16 v[96:99], v[156:159], v[172:175], v[96:99]
	v_mfma_f32_16x16x32_bf16 v[84:87], v[148:151], v[180:183], v[84:87]
	v_mfma_f32_16x16x32_bf16 v[80:83], v[156:159], v[180:183], v[80:83]
	v_mfma_f32_16x16x32_bf16 v[68:71], v[148:151], v[216:219], v[68:71]
	v_mfma_f32_16x16x32_bf16 v[64:67], v[156:159], v[216:219], v[64:67]
	s_setprio 0
	s_barrier
	s_add_i32 s56, s68, s3
	v_lshl_add_u64 v[220:221], s[58:59], 0, v[186:187]
	s_mov_b32 m0, s56
	ds_read_b128 v[160:163], v232 offset:16384
	ds_read_b128 v[164:167], v232 offset:17408
	ds_read_b128 v[168:171], v232 offset:18432
	ds_read_b128 v[172:175], v232 offset:19456
	ds_read_b128 v[176:179], v232 offset:20480
	ds_read_b128 v[180:183], v232 offset:21504
	ds_read_b128 v[212:215], v232 offset:22528
	ds_read_b128 v[216:219], v232 offset:23552
	global_load_lds_dwordx4 v[220:221], off
	s_add_i32 m0, s56, 0x2000
	s_add_u32 s56, s58, 0x30000
	v_lshl_add_u64 v[222:223], s[58:59], 0, v[190:191]
	s_addc_u32 s57, s59, 0
	s_add_i32 s83, s69, s3
	global_load_lds_dwordx4 v[222:223], off
	v_lshl_add_u64 v[224:225], s[56:57], 0, v[186:187]
	s_mov_b32 m0, s83
	v_lshl_add_u64 v[234:235], s[60:61], 0, v[188:189]
	global_load_lds_dwordx4 v[224:225], off
	v_lshl_add_u64 v[224:225], s[56:57], 0, v[190:191]
	s_add_i32 m0, s83, 0x2000
	s_nop 0
	global_load_lds_dwordx4 v[224:225], off
	v_lshl_add_u64 v[224:225], s[60:61], 0, v[184:185]
	s_mov_b32 m0, s25
	s_nop 0
	global_load_lds_dwordx4 v[224:225], off
	s_mov_b32 m0, s33
	s_nop 0
	global_load_lds_dwordx4 v[234:235], off
	s_waitcnt vmcnt(8)
	s_waitcnt lgkmcnt(0)
	s_barrier
; #define PG8_STAGE(bufoff, gbase, voff) do { _Pragma("unroll") for (int _i = 0; _i < 2; ++_i) \
;         __builtin_amdgcn_global_load_lds((const unsigned*)((const char*)(gbase) + (voff)[_i]), (PG8_LAS unsigned*)(lds + (bufoff) + ldsw + _i * 8192), 16, 0, 0); } while (0)
; #define PG8_LDA(dst, b, h) do { _Pragma("unroll") for (int m = 0; m < 4; ++m) _Pragma("unroll") for (int k = 0; k < 2; ++k) dst[m][k] = *(const PG8_LAS bf16x8*)(lds + PG8_SA(b, h) + aoff + m * 2048 + k * 1024); } while (0)
; #define PG8_LDB(dst, b, h) do { _Pragma("unroll") for (int n = 0; n < 2; ++n) _Pragma("unroll") for (int k = 0; k < 2; ++k) dst[n][k] = *(const PG8_LAS bf16x8*)(lds + PG8_SB(b, h) + boff + n * 2048 + k * 1024); } while (0)
; #define PG8_MMA(ai, bj, At, Bt) do { __builtin_amdgcn_s_setprio(1); _Pragma("unroll") for (int m = 0; m < 4; ++m) _Pragma("unroll") for (int n = 0; n < 2; ++n) _Pragma("unroll") for (int k = 0; k < 2; ++k) \
;         acc[ai][bj][m][n] = __builtin_amdgcn_mfma_f32_16x16x32_bf16(Bt[n][k], At[m][k], acc[ai][bj][m][n], 0, 0, 0); __builtin_amdgcn_s_setprio(0); } while (0)
; #define PG8_WAIT_V(n) asm volatile("s_waitcnt vmcnt(" #n ")" ::: "memory")
; #define PG8_WAIT_L(n) asm volatile("s_waitcnt lgkmcnt(" #n ")" ::: "memory")
; #define PG8_BAR __builtin_amdgcn_s_barrier()
; #define PG8_SCHED __builtin_amdgcn_sched_barrier(0)
; template <class Epi, class Sched, bool ALIGN_EPI = false, bool SP2 = false>
; __device__ __forceinline__ void gemm_phase(PG8_LAS unsigned char* lds, const Gemm g, const Sched& S, const Epi& E) {
;     ...
;             PG8_WAIT_V(8); PG8_WAIT_L(0); PG8_BAR; PG8_MMA(1, 0, At, B0); PG8_MMA(1, 1, At, B1); PG8_BAR; PG8_SCHED;
;             PG8_LDB(B0, 1, 0); PG8_LDB(B1, 1, 1); PG8_SCHED; PG8_LDA(At, 1, 0); PG8_STAGE(PG8_SA(0, 1), a2 + hstep, voffA);
;             PG8_WAIT_V(8); PG8_WAIT_L(0); PG8_BAR; PG8_MMA(0, 0, At, B0); PG8_MMA(0, 1, At, B1); PG8_BAR; PG8_SCHED;
	s_setprio 1
	s_waitcnt lgkmcnt(0)
	v_mfma_f32_16x16x32_bf16 v[60:63], v[128:131], v[160:163], v[60:63]
	v_mfma_f32_16x16x32_bf16 v[56:59], v[136:139], v[160:163], v[56:59]
	v_mfma_f32_16x16x32_bf16 v[44:47], v[128:131], v[168:171], v[44:47]
	v_mfma_f32_16x16x32_bf16 v[40:43], v[136:139], v[168:171], v[40:43]
	v_mfma_f32_16x16x32_bf16 v[28:31], v[128:131], v[176:179], v[28:31]
	v_mfma_f32_16x16x32_bf16 v[24:27], v[136:139], v[176:179], v[24:27]
	v_mfma_f32_16x16x32_bf16 v[12:15], v[128:131], v[212:215], v[12:15]
	v_mfma_f32_16x16x32_bf16 v[8:11], v[136:139], v[212:215], v[8:11]
	v_mfma_f32_16x16x32_bf16 v[60:63], v[132:135], v[164:167], v[60:63]
	v_mfma_f32_16x16x32_bf16 v[56:59], v[140:143], v[164:167], v[56:59]
	v_mfma_f32_16x16x32_bf16 v[44:47], v[132:135], v[172:175], v[44:47]
	v_mfma_f32_16x16x32_bf16 v[40:43], v[140:143], v[172:175], v[40:43]
	v_mfma_f32_16x16x32_bf16 v[28:31], v[132:135], v[180:183], v[28:31]
	v_mfma_f32_16x16x32_bf16 v[24:27], v[140:143], v[180:183], v[24:27]
	v_mfma_f32_16x16x32_bf16 v[12:15], v[132:135], v[216:219], v[12:15]
	v_mfma_f32_16x16x32_bf16 v[8:11], v[140:143], v[216:219], v[8:11]
	s_setprio 0
	s_setprio 1
	v_mfma_f32_16x16x32_bf16 v[52:55], v[144:147], v[160:163], v[52:55]
	v_mfma_f32_16x16x32_bf16 v[48:51], v[152:155], v[160:163], v[48:51]
	v_mfma_f32_16x16x32_bf16 v[36:39], v[144:147], v[168:171], v[36:39]
	v_mfma_f32_16x16x32_bf16 v[32:35], v[152:155], v[168:171], v[32:35]
	v_mfma_f32_16x16x32_bf16 v[20:23], v[144:147], v[176:179], v[20:23]
	v_mfma_f32_16x16x32_bf16 v[16:19], v[152:155], v[176:179], v[16:19]
	v_mfma_f32_16x16x32_bf16 v[4:7], v[144:147], v[212:215], v[4:7]
	v_mfma_f32_16x16x32_bf16 v[0:3], v[152:155], v[212:215], v[0:3]
	v_mfma_f32_16x16x32_bf16 v[52:55], v[148:151], v[164:167], v[52:55]
	v_mfma_f32_16x16x32_bf16 v[48:51], v[156:159], v[164:167], v[48:51]
	v_mfma_f32_16x16x32_bf16 v[36:39], v[148:151], v[172:175], v[36:39]
	v_mfma_f32_16x16x32_bf16 v[32:35], v[156:159], v[172:175], v[32:35]
	v_mfma_f32_16x16x32_bf16 v[20:23], v[148:151], v[180:183], v[20:23]
	v_mfma_f32_16x16x32_bf16 v[16:19], v[156:159], v[180:183], v[16:19]
	v_mfma_f32_16x16x32_bf16 v[4:7], v[148:151], v[216:219], v[4:7]
	v_mfma_f32_16x16x32_bf16 v[0:3], v[156:159], v[216:219], v[0:3]
	s_setprio 0
	s_barrier
	s_add_i32 s83, 0, 0x18000
	s_add_i32 s84, 0, 0x1c000
	v_add_u32_e32 v140, s83, v227
	v_add_u32_e32 v156, s84, v227
	ds_read_b128 v[128:131], v140
	ds_read_b128 v[132:135], v140 offset:1024
	ds_read_b128 v[136:139], v140 offset:2048
	ds_read_b128 v[140:143], v140 offset:3072
	ds_read_b128 v[144:147], v156
	ds_read_b128 v[148:151], v156 offset:1024
	ds_read_b128 v[152:155], v156 offset:2048
	ds_read_b128 v[156:159], v156 offset:3072
	s_add_u32 s56, s60, 0x30000
	s_addc_u32 s57, s61, 0
	s_mov_b32 m0, s34
	v_lshl_add_u64 v[236:237], s[56:57], 0, v[184:185]
	ds_read_b128 v[160:163], v232 offset:32768
	ds_read_b128 v[164:167], v232 offset:33792
	ds_read_b128 v[168:171], v232 offset:34816
	ds_read_b128 v[172:175], v232 offset:35840
	ds_read_b128 v[176:179], v232 offset:36864
	ds_read_b128 v[180:183], v232 offset:37888
	ds_read_b128 v[212:215], v232 offset:38912
	ds_read_b128 v[216:219], v232 offset:39936
	global_load_lds_dwordx4 v[236:237], off
	v_lshl_add_u64 v[236:237], s[56:57], 0, v[188:189]
	s_mov_b32 m0, s35
	s_nop 0
	global_load_lds_dwordx4 v[236:237], off
	s_waitcnt vmcnt(8)
	s_waitcnt lgkmcnt(0)
	s_barrier
	s_setprio 1
	s_waitcnt lgkmcnt(0)
	v_mfma_f32_16x16x32_bf16 v[124:127], v[128:131], v[160:163], v[124:127]
	v_mfma_f32_16x16x32_bf16 v[120:123], v[136:139], v[160:163], v[120:123]
	v_mfma_f32_16x16x32_bf16 v[108:111], v[128:131], v[168:171], v[108:111]
	v_mfma_f32_16x16x32_bf16 v[104:107], v[136:139], v[168:171], v[104:107]
	v_mfma_f32_16x16x32_bf16 v[92:95], v[128:131], v[176:179], v[92:95]
	v_mfma_f32_16x16x32_bf16 v[88:91], v[136:139], v[176:179], v[88:91]
	v_mfma_f32_16x16x32_bf16 v[76:79], v[128:131], v[212:215], v[76:79]
	v_mfma_f32_16x16x32_bf16 v[72:75], v[136:139], v[212:215], v[72:75]
	v_mfma_f32_16x16x32_bf16 v[124:127], v[132:135], v[164:167], v[124:127]
	v_mfma_f32_16x16x32_bf16 v[120:123], v[140:143], v[164:167], v[120:123]
	v_mfma_f32_16x16x32_bf16 v[108:111], v[132:135], v[172:175], v[108:111]
	v_mfma_f32_16x16x32_bf16 v[104:107], v[140:143], v[172:175], v[104:107]
	v_mfma_f32_16x16x32_bf16 v[92:95], v[132:135], v[180:183], v[92:95]
	v_mfma_f32_16x16x32_bf16 v[88:91], v[140:143], v[180:183], v[88:91]
	v_mfma_f32_16x16x32_bf16 v[76:79], v[132:135], v[216:219], v[76:79]
	v_mfma_f32_16x16x32_bf16 v[72:75], v[140:143], v[216:219], v[72:75]
	s_setprio 0
	s_setprio 1
	v_mfma_f32_16x16x32_bf16 v[116:119], v[144:147], v[160:163], v[116:119]
	v_mfma_f32_16x16x32_bf16 v[112:115], v[152:155], v[160:163], v[112:115]
	v_mfma_f32_16x16x32_bf16 v[100:103], v[144:147], v[168:171], v[100:103]
	v_mfma_f32_16x16x32_bf16 v[96:99], v[152:155], v[168:171], v[96:99]
	v_mfma_f32_16x16x32_bf16 v[84:87], v[144:147], v[176:179], v[84:87]
	v_mfma_f32_16x16x32_bf16 v[80:83], v[152:155], v[176:179], v[80:83]
	v_mfma_f32_16x16x32_bf16 v[68:71], v[144:147], v[212:215], v[68:71]
	v_mfma_f32_16x16x32_bf16 v[64:67], v[152:155], v[212:215], v[64:67]
	v_mfma_f32_16x16x32_bf16 v[116:119], v[148:151], v[164:167], v[116:119]
	v_mfma_f32_16x16x32_bf16 v[112:115], v[156:159], v[164:167], v[112:115]
	v_mfma_f32_16x16x32_bf16 v[100:103], v[148:151], v[172:175], v[100:103]
	v_mfma_f32_16x16x32_bf16 v[96:99], v[156:159], v[172:175], v[96:99]
	v_mfma_f32_16x16x32_bf16 v[84:87], v[148:151], v[180:183], v[84:87]
	v_mfma_f32_16x16x32_bf16 v[80:83], v[156:159], v[180:183], v[80:83]
	v_mfma_f32_16x16x32_bf16 v[68:71], v[148:151], v[216:219], v[68:71]
	v_mfma_f32_16x16x32_bf16 v[64:67], v[156:159], v[216:219], v[64:67]
	s_setprio 0
	s_barrier
; #define PG8_STAGE(bufoff, gbase, voff) do { _Pragma("unroll") for (int _i = 0; _i < 2; ++_i) \
;         __builtin_amdgcn_global_load_lds((const unsigned*)((const char*)(gbase) + (voff)[_i]), (PG8_LAS unsigned*)(lds + (bufoff) + ldsw + _i * 8192), 16, 0, 0); } while (0)
; #define PG8_LDA(dst, b, h) do { _Pragma("unroll") for (int m = 0; m < 4; ++m) _Pragma("unroll") for (int k = 0; k < 2; ++k) dst[m][k] = *(const PG8_LAS bf16x8*)(lds + PG8_SA(b, h) + aoff + m * 2048 + k * 1024); } while (0)
; #define PG8_MMA(ai, bj, At, Bt) do { __builtin_amdgcn_s_setprio(1); _Pragma("unroll") for (int m = 0; m < 4; ++m) _Pragma("unroll") for (int n = 0; n < 2; ++n) _Pragma("unroll") for (int k = 0; k < 2; ++k) \
;         acc[ai][bj][m][n] = __builtin_amdgcn_mfma_f32_16x16x32_bf16(Bt[n][k], At[m][k], acc[ai][bj][m][n], 0, 0, 0); __builtin_amdgcn_s_setprio(0); } while (0)
; #define PG8_WAIT_V(n) asm volatile("s_waitcnt vmcnt(" #n ")" ::: "memory")
; #define PG8_WAIT_L(n) asm volatile("s_waitcnt lgkmcnt(" #n ")" ::: "memory")
; #define PG8_BAR __builtin_amdgcn_s_barrier()
; #define PG8_SCHED __builtin_amdgcn_sched_barrier(0)
; template <class Epi, class Sched, bool ALIGN_EPI = false, bool SP2 = false>
; __device__ __forceinline__ void gemm_phase(PG8_LAS unsigned char* lds, const Gemm g, const Sched& S, const Epi& E) {
;     ...
;         for (int t = 0; t < nt; t += 2) {
;     ...
;             PG8_LDA(At, 1, 1); PG8_STAGE(PG8_SB(1, 0), b3, voffB); PG8_STAGE(PG8_SB(1, 1), b3 + hstep, voffB); PG8_STAGE(PG8_SA(1, 0), a3, voffA);
;             PG8_WAIT_V(8); PG8_WAIT_L(0); PG8_BAR; PG8_MMA(1, 0, At, B0); PG8_MMA(1, 1, At, B1); PG8_BAR; PG8_SCHED;
	s_add_i32 s56, s83, s3
	v_lshl_add_u64 v[220:221], v[220:221], 0, s[38:39]
	s_mov_b32 m0, s56
	ds_read_b128 v[160:163], v232 offset:49152
	ds_read_b128 v[164:167], v232 offset:50176
	ds_read_b128 v[168:171], v232 offset:51200
	ds_read_b128 v[172:175], v232 offset:52224
	ds_read_b128 v[176:179], v232 offset:53248
	ds_read_b128 v[180:183], v232 offset:54272
	ds_read_b128 v[212:215], v232 offset:55296
	ds_read_b128 v[216:219], v232 offset:56320
	global_load_lds_dwordx4 v[220:221], off
	s_add_i32 m0, s56, 0x2000
	s_add_u32 s56, s58, 0x30080
	v_lshl_add_u64 v[220:221], v[222:223], 0, s[38:39]
	s_addc_u32 s57, s59, 0
	s_add_i32 s58, s84, s3
	global_load_lds_dwordx4 v[220:221], off
	v_lshl_add_u64 v[220:221], s[56:57], 0, v[186:187]
	s_mov_b32 m0, s58
	s_nop 0
	global_load_lds_dwordx4 v[220:221], off
	v_lshl_add_u64 v[220:221], s[56:57], 0, v[190:191]
	s_add_i32 m0, s58, 0x2000
	s_nop 0
	global_load_lds_dwordx4 v[220:221], off
	v_lshl_add_u64 v[220:221], v[224:225], 0, s[38:39]
	s_mov_b32 m0, s63
	s_nop 0
	global_load_lds_dwordx4 v[220:221], off
	v_lshl_add_u64 v[220:221], v[234:235], 0, s[38:39]
	s_mov_b32 m0, s64
	s_nop 0
	global_load_lds_dwordx4 v[220:221], off
	s_waitcnt vmcnt(8)
	s_waitcnt lgkmcnt(0)
	s_barrier
	s_setprio 1
	s_waitcnt lgkmcnt(0)
	v_mfma_f32_16x16x32_bf16 v[60:63], v[128:131], v[160:163], v[60:63]
	v_mfma_f32_16x16x32_bf16 v[56:59], v[136:139], v[160:163], v[56:59]
	v_mfma_f32_16x16x32_bf16 v[44:47], v[128:131], v[168:171], v[44:47]
	v_mfma_f32_16x16x32_bf16 v[40:43], v[136:139], v[168:171], v[40:43]
	v_mfma_f32_16x16x32_bf16 v[28:31], v[128:131], v[176:179], v[28:31]
	v_mfma_f32_16x16x32_bf16 v[24:27], v[136:139], v[176:179], v[24:27]
	v_mfma_f32_16x16x32_bf16 v[12:15], v[128:131], v[212:215], v[12:15]
	v_mfma_f32_16x16x32_bf16 v[8:11], v[136:139], v[212:215], v[8:11]
	v_mfma_f32_16x16x32_bf16 v[60:63], v[132:135], v[164:167], v[60:63]
	v_mfma_f32_16x16x32_bf16 v[56:59], v[140:143], v[164:167], v[56:59]
	v_mfma_f32_16x16x32_bf16 v[44:47], v[132:135], v[172:175], v[44:47]
	v_mfma_f32_16x16x32_bf16 v[40:43], v[140:143], v[172:175], v[40:43]
	v_mfma_f32_16x16x32_bf16 v[28:31], v[132:135], v[180:183], v[28:31]
	v_mfma_f32_16x16x32_bf16 v[24:27], v[140:143], v[180:183], v[24:27]
	v_mfma_f32_16x16x32_bf16 v[12:15], v[132:135], v[216:219], v[12:15]
	v_mfma_f32_16x16x32_bf16 v[8:11], v[140:143], v[216:219], v[8:11]
	s_setprio 0
	s_setprio 1
	v_mfma_f32_16x16x32_bf16 v[52:55], v[144:147], v[160:163], v[52:55]
	v_mfma_f32_16x16x32_bf16 v[48:51], v[152:155], v[160:163], v[48:51]
	v_mfma_f32_16x16x32_bf16 v[36:39], v[144:147], v[168:171], v[36:39]
	v_mfma_f32_16x16x32_bf16 v[32:35], v[152:155], v[168:171], v[32:35]
	v_mfma_f32_16x16x32_bf16 v[20:23], v[144:147], v[176:179], v[20:23]
	v_mfma_f32_16x16x32_bf16 v[16:19], v[152:155], v[176:179], v[16:19]
	v_mfma_f32_16x16x32_bf16 v[4:7], v[144:147], v[212:215], v[4:7]
	v_mfma_f32_16x16x32_bf16 v[0:3], v[152:155], v[212:215], v[0:3]
	v_mfma_f32_16x16x32_bf16 v[52:55], v[148:151], v[164:167], v[52:55]
	v_mfma_f32_16x16x32_bf16 v[48:51], v[156:159], v[164:167], v[48:51]
	v_mfma_f32_16x16x32_bf16 v[36:39], v[148:151], v[172:175], v[36:39]
	v_mfma_f32_16x16x32_bf16 v[32:35], v[156:159], v[172:175], v[32:35]
	v_mfma_f32_16x16x32_bf16 v[20:23], v[148:151], v[180:183], v[20:23]
	v_mfma_f32_16x16x32_bf16 v[16:19], v[156:159], v[180:183], v[16:19]
	v_mfma_f32_16x16x32_bf16 v[4:7], v[148:151], v[216:219], v[4:7]
	v_mfma_f32_16x16x32_bf16 v[0:3], v[156:159], v[216:219], v[0:3]
	s_setprio 0
	s_barrier
	s_add_i32 s82, s82, 2
	s_add_u32 s80, s80, 0x100
	s_addc_u32 s81, s81, 0
	s_cmp_gt_u32 s82, 9
	s_mov_b64 s[56:57], s[0:1]
	s_cbranch_scc0 .LBB0_382
	s_and_b64 vcc, exec, s[40:41]
	s_cbranch_vccz .LBB0_385
	s_barrier
